# s5 E@U: direction 1's first eight E fragments requested at the end of direction 0's carry phase (plus packed carry scan)
# baseline (speedup 1.0000x reference)
.LBB0_719:
	v_add_u32_e32 v34, s88, v119
	v_lshrrev_b32_e32 v35, 5, v34
	v_and_b32_e32 v34, 31, v34
	v_lshlrev_b32_e32 v34, 5, v34
	v_lshl_add_u32 v34, v35, 14, v34
	v_add_u32_e32 v34, 0x1000, v34
	v_mov_b32_e32 v35, v33
	v_lshl_add_u64 v[34:35], v[150:151], 0, v[34:35]
	v_mov_b32_e32 v44, 0x2000
	v_mov_b32_e32 v45, v33
	v_lshl_add_u64 v[44:45], v[34:35], 0, v[44:45]
	v_add_u32_e32 v32, v139, v141
	ds_read_b128 v[246:249], v32
	ds_read_b128 v[250:253], v32 offset:16896
	ds_read_b128 v[36:39], v32 offset:32
	ds_read_b128 v[40:43], v32 offset:16928
	s_waitcnt vmcnt(7) lgkmcnt(3)
	v_mfma_f32_32x32x16_bf16 v[96:111], v[166:169], v[246:249], 0
	ds_read_b128 v[246:249], v32 offset:64
	s_waitcnt lgkmcnt(3)
	v_mfma_f32_32x32x16_bf16 v[80:95], v[166:169], v[250:253], 0
	ds_read_b128 v[250:253], v32 offset:16960
	global_load_dwordx4 v[166:169], v[44:45], off offset:-4096
	s_waitcnt vmcnt(7) lgkmcnt(3)
	v_mfma_f32_32x32x16_bf16 v[96:111], v[170:173], v[36:39], v[96:111]
	ds_read_b128 v[36:39], v32 offset:96
	s_waitcnt lgkmcnt(3)
	v_mfma_f32_32x32x16_bf16 v[80:95], v[170:173], v[40:43], v[80:95]
	ds_read_b128 v[40:43], v32 offset:16992
	global_load_dwordx4 v[170:173], v[44:45], off offset:-3072
	s_waitcnt vmcnt(7) lgkmcnt(3)
	v_mfma_f32_32x32x16_bf16 v[96:111], v[174:177], v[246:249], v[96:111]
	ds_read_b128 v[246:249], v32 offset:128
	s_waitcnt lgkmcnt(3)
	v_mfma_f32_32x32x16_bf16 v[80:95], v[174:177], v[250:253], v[80:95]
	ds_read_b128 v[250:253], v32 offset:17024
	global_load_dwordx4 v[174:177], v[44:45], off offset:-2048
	s_waitcnt vmcnt(7) lgkmcnt(3)
	v_mfma_f32_32x32x16_bf16 v[96:111], v[190:193], v[36:39], v[96:111]
	ds_read_b128 v[36:39], v32 offset:160
	s_waitcnt lgkmcnt(3)
	v_mfma_f32_32x32x16_bf16 v[80:95], v[190:193], v[40:43], v[80:95]
	ds_read_b128 v[40:43], v32 offset:17056
	global_load_dwordx4 v[190:193], v[44:45], off offset:-1024
	s_waitcnt vmcnt(7) lgkmcnt(3)
	v_mfma_f32_32x32x16_bf16 v[96:111], v[194:197], v[246:249], v[96:111]
	ds_read_b128 v[246:249], v32 offset:192
	s_waitcnt lgkmcnt(3)
	v_mfma_f32_32x32x16_bf16 v[80:95], v[194:197], v[250:253], v[80:95]
	ds_read_b128 v[250:253], v32 offset:17088
	global_load_dwordx4 v[194:197], v[44:45], off offset:0
	s_waitcnt vmcnt(7) lgkmcnt(3)
	v_mfma_f32_32x32x16_bf16 v[96:111], v[198:201], v[36:39], v[96:111]
	ds_read_b128 v[36:39], v32 offset:224
	s_waitcnt lgkmcnt(3)
	v_mfma_f32_32x32x16_bf16 v[80:95], v[198:201], v[40:43], v[80:95]
	ds_read_b128 v[40:43], v32 offset:17120
	global_load_dwordx4 v[198:201], v[44:45], off offset:1024
	s_waitcnt vmcnt(7) lgkmcnt(3)
	v_mfma_f32_32x32x16_bf16 v[96:111], v[202:205], v[246:249], v[96:111]
	ds_read_b128 v[246:249], v32 offset:256
	s_waitcnt lgkmcnt(3)
	v_mfma_f32_32x32x16_bf16 v[80:95], v[202:205], v[250:253], v[80:95]
	ds_read_b128 v[250:253], v32 offset:17152
	global_load_dwordx4 v[202:205], v[44:45], off offset:2048
	s_waitcnt vmcnt(7) lgkmcnt(3)
	v_mfma_f32_32x32x16_bf16 v[96:111], v[206:209], v[36:39], v[96:111]
	ds_read_b128 v[36:39], v32 offset:288
	s_waitcnt lgkmcnt(3)
	v_mfma_f32_32x32x16_bf16 v[80:95], v[206:209], v[40:43], v[80:95]
	ds_read_b128 v[40:43], v32 offset:17184
	global_load_dwordx4 v[206:209], v[44:45], off offset:3072
	s_waitcnt vmcnt(7) lgkmcnt(3)
	v_mfma_f32_32x32x16_bf16 v[96:111], v[166:169], v[246:249], v[96:111]
	ds_read_b128 v[246:249], v32 offset:320
	s_waitcnt lgkmcnt(3)
	v_mfma_f32_32x32x16_bf16 v[80:95], v[166:169], v[250:253], v[80:95]
	ds_read_b128 v[250:253], v32 offset:17216
	s_waitcnt vmcnt(6) lgkmcnt(3)
	v_mfma_f32_32x32x16_bf16 v[96:111], v[170:173], v[36:39], v[96:111]
	ds_read_b128 v[36:39], v32 offset:352
	s_waitcnt lgkmcnt(3)
	v_mfma_f32_32x32x16_bf16 v[80:95], v[170:173], v[40:43], v[80:95]
	ds_read_b128 v[40:43], v32 offset:17248
	s_waitcnt vmcnt(5) lgkmcnt(3)
	v_mfma_f32_32x32x16_bf16 v[96:111], v[174:177], v[246:249], v[96:111]
	ds_read_b128 v[246:249], v32 offset:384
	s_waitcnt lgkmcnt(3)
	v_mfma_f32_32x32x16_bf16 v[80:95], v[174:177], v[250:253], v[80:95]
	ds_read_b128 v[250:253], v32 offset:17280
	s_waitcnt vmcnt(4) lgkmcnt(3)
	v_mfma_f32_32x32x16_bf16 v[96:111], v[190:193], v[36:39], v[96:111]
	ds_read_b128 v[36:39], v32 offset:416
	s_waitcnt lgkmcnt(3)
	v_mfma_f32_32x32x16_bf16 v[80:95], v[190:193], v[40:43], v[80:95]
	ds_read_b128 v[40:43], v32 offset:17312
	s_waitcnt vmcnt(3) lgkmcnt(3)
	v_mfma_f32_32x32x16_bf16 v[96:111], v[194:197], v[246:249], v[96:111]
	ds_read_b128 v[246:249], v32 offset:448
	s_waitcnt lgkmcnt(3)
	v_mfma_f32_32x32x16_bf16 v[80:95], v[194:197], v[250:253], v[80:95]
	ds_read_b128 v[250:253], v32 offset:17344
	s_waitcnt vmcnt(2) lgkmcnt(3)
	v_mfma_f32_32x32x16_bf16 v[96:111], v[198:201], v[36:39], v[96:111]
	ds_read_b128 v[36:39], v32 offset:480
	s_waitcnt lgkmcnt(3)
	v_mfma_f32_32x32x16_bf16 v[80:95], v[198:201], v[40:43], v[80:95]
	ds_read_b128 v[40:43], v32 offset:17376
	s_waitcnt vmcnt(1) lgkmcnt(3)
	v_mfma_f32_32x32x16_bf16 v[96:111], v[202:205], v[246:249], v[96:111]
	s_waitcnt lgkmcnt(2)
	v_mfma_f32_32x32x16_bf16 v[80:95], v[202:205], v[250:253], v[80:95]
	s_waitcnt vmcnt(0) lgkmcnt(1)
	v_mfma_f32_32x32x16_bf16 v[96:111], v[206:209], v[36:39], v[96:111]
	s_waitcnt lgkmcnt(0)
	v_mfma_f32_32x32x16_bf16 v[80:95], v[206:209], v[40:43], v[80:95]
	s_nop 15
	ds_write_b128 v165, v[96:99]
	ds_write_b128 v165, v[100:103] offset:32
	ds_write_b128 v165, v[104:107] offset:64
	ds_write_b128 v165, v[108:111] offset:96
	ds_write_b128 v165, v[80:83] offset:16896
	ds_write_b128 v165, v[84:87] offset:16928
	ds_write_b128 v165, v[88:91] offset:16960
	ds_write_b128 v165, v[92:95] offset:16992
	s_waitcnt lgkmcnt(0)
	s_barrier
	s_and_b64 s[30:31], s[10:11], exec
	s_cbranch_scc0 .Ls5_nopf
	v_mov_b32_e32 v34, 0x2000
	v_mov_b32_e32 v35, v33
	v_lshl_add_u64 v[34:35], v[148:149], 0, v[34:35]
	global_load_dwordx4 v[100:103], v[148:149], off offset:-4096
	global_load_dwordx4 v[104:107], v[148:149], off offset:-3072
	global_load_dwordx4 v[108:111], v[148:149], off offset:-2048
	global_load_dwordx4 v[166:169], v[148:149], off offset:-1024
	global_load_dwordx4 v[170:173], v[148:149], off offset:0
	global_load_dwordx4 v[174:177], v[148:149], off offset:1024
	global_load_dwordx4 v[190:193], v[148:149], off offset:2048
	global_load_dwordx4 v[194:197], v[148:149], off offset:3072
	global_load_dwordx4 v[198:201], v[34:35], off offset:-4096
	global_load_dwordx4 v[202:205], v[34:35], off offset:-3072
	global_load_dwordx4 v[206:209], v[34:35], off offset:-2048
	global_load_dwordx4 v[234:237], v[34:35], off offset:-1024
	global_load_dwordx4 v[238:241], v[34:35], off offset:0
	global_load_dwordx4 v[242:245], v[34:35], off offset:1024
	global_load_dwordx4 v[246:249], v[34:35], off offset:2048
	global_load_dwordx4 v[250:253], v[34:35], off offset:3072

.LBB0_724:
	s_lshl_b32 s24, s88, 6
	v_mov_b32_e32 v38, s24
	v_mov_b32_e32 v39, v33
	v_lshl_add_u64 v[38:39], v[152:153], 0, v[38:39]
	global_load_dwordx4 v[100:103], v[38:39], off offset:-4096
	global_load_dwordx4 v[104:107], v[38:39], off offset:-3072
	global_load_dwordx4 v[108:111], v[38:39], off offset:-2048
	global_load_dwordx4 v[166:169], v[38:39], off offset:-1024
	global_load_dwordx4 v[170:173], v[38:39], off
	global_load_dwordx4 v[174:177], v[38:39], off offset:1024
	global_load_dwordx4 v[190:193], v[38:39], off offset:2048
	global_load_dwordx4 v[194:197], v[38:39], off offset:3072
	v_add_u32_e32 v32, 0x10800, v156
	s_waitcnt lgkmcnt(0)
	s_barrier
	ds_read_b128 v[198:201], v32
	ds_read_b128 v[202:205], v32 offset:16
	ds_read_b128 v[206:209], v32 offset:16896
	ds_read_b128 v[234:237], v32 offset:16912
	ds_read_b128 v[238:241], v32 offset:33792
	ds_read_b128 v[242:245], v32 offset:33808
	s_waitcnt vmcnt(7) lgkmcnt(4)
	v_cvt_pk_bf16_f32 v246, v198, v199
	v_cvt_pk_bf16_f32 v247, v200, v201
	v_cvt_pk_bf16_f32 v248, v202, v203
	v_cvt_pk_bf16_f32 v249, v204, v205
	s_nop 1
	v_mfma_f32_32x32x16_bf16 v[64:79], v[100:103], v[246:249], v[64:79]
	ds_read_b128 v[198:201], v32 offset:50688
	ds_read_b128 v[202:205], v32 offset:50704
	s_waitcnt lgkmcnt(4)
	v_cvt_pk_bf16_f32 v250, v206, v207
	v_cvt_pk_bf16_f32 v251, v208, v209
	v_cvt_pk_bf16_f32 v252, v234, v235
	v_cvt_pk_bf16_f32 v253, v236, v237
	s_nop 1
	v_mfma_f32_32x32x16_bf16 v[48:63], v[100:103], v[250:253], v[48:63]
	ds_read_b128 v[206:209], v32 offset:64
	ds_read_b128 v[234:237], v32 offset:80
	s_waitcnt lgkmcnt(4)
	v_cvt_pk_bf16_f32 v246, v238, v239
	v_cvt_pk_bf16_f32 v247, v240, v241
	v_cvt_pk_bf16_f32 v248, v242, v243
	v_cvt_pk_bf16_f32 v249, v244, v245
	s_nop 1
	v_mfma_f32_32x32x16_bf16 v[16:31], v[100:103], v[246:249], v[16:31]
	ds_read_b128 v[238:241], v32 offset:16960
	ds_read_b128 v[242:245], v32 offset:16976
	s_waitcnt lgkmcnt(4)
	v_cvt_pk_bf16_f32 v250, v198, v199
	v_cvt_pk_bf16_f32 v251, v200, v201
	v_cvt_pk_bf16_f32 v252, v202, v203
	v_cvt_pk_bf16_f32 v253, v204, v205
	s_nop 1
	v_mfma_f32_32x32x16_bf16 v[0:15], v[100:103], v[250:253], v[0:15]
	ds_read_b128 v[198:201], v32 offset:33856
	ds_read_b128 v[202:205], v32 offset:33872
	s_waitcnt vmcnt(6) lgkmcnt(4)
	v_cvt_pk_bf16_f32 v246, v206, v207
	v_cvt_pk_bf16_f32 v247, v208, v209
	v_cvt_pk_bf16_f32 v248, v234, v235
	v_cvt_pk_bf16_f32 v249, v236, v237
	s_nop 1
	v_mfma_f32_32x32x16_bf16 v[64:79], v[104:107], v[246:249], v[64:79]
	ds_read_b128 v[206:209], v32 offset:50752
	ds_read_b128 v[234:237], v32 offset:50768
	s_waitcnt lgkmcnt(4)
	v_cvt_pk_bf16_f32 v250, v238, v239
	v_cvt_pk_bf16_f32 v251, v240, v241
	v_cvt_pk_bf16_f32 v252, v242, v243
	v_cvt_pk_bf16_f32 v253, v244, v245
	s_nop 1
	v_mfma_f32_32x32x16_bf16 v[48:63], v[104:107], v[250:253], v[48:63]
	ds_read_b128 v[238:241], v32 offset:128
	ds_read_b128 v[242:245], v32 offset:144
	s_waitcnt lgkmcnt(4)
	v_cvt_pk_bf16_f32 v246, v198, v199
	v_cvt_pk_bf16_f32 v247, v200, v201
	v_cvt_pk_bf16_f32 v248, v202, v203
	v_cvt_pk_bf16_f32 v249, v204, v205
	s_nop 1
	v_mfma_f32_32x32x16_bf16 v[16:31], v[104:107], v[246:249], v[16:31]
	ds_read_b128 v[198:201], v32 offset:17024
	ds_read_b128 v[202:205], v32 offset:17040
	s_waitcnt lgkmcnt(4)
	v_cvt_pk_bf16_f32 v250, v206, v207
	v_cvt_pk_bf16_f32 v251, v208, v209
	v_cvt_pk_bf16_f32 v252, v234, v235
	v_cvt_pk_bf16_f32 v253, v236, v237
	s_nop 1
	v_mfma_f32_32x32x16_bf16 v[0:15], v[104:107], v[250:253], v[0:15]
	ds_read_b128 v[206:209], v32 offset:33920
	ds_read_b128 v[234:237], v32 offset:33936
	s_waitcnt vmcnt(5) lgkmcnt(4)
	v_cvt_pk_bf16_f32 v246, v238, v239
	v_cvt_pk_bf16_f32 v247, v240, v241
	v_cvt_pk_bf16_f32 v248, v242, v243
	v_cvt_pk_bf16_f32 v249, v244, v245
	s_nop 1
	v_mfma_f32_32x32x16_bf16 v[64:79], v[108:111], v[246:249], v[64:79]
	ds_read_b128 v[238:241], v32 offset:50816
	ds_read_b128 v[242:245], v32 offset:50832
	s_waitcnt lgkmcnt(4)
	v_cvt_pk_bf16_f32 v250, v198, v199
	v_cvt_pk_bf16_f32 v251, v200, v201
	v_cvt_pk_bf16_f32 v252, v202, v203
	v_cvt_pk_bf16_f32 v253, v204, v205
	s_nop 1
	v_mfma_f32_32x32x16_bf16 v[48:63], v[108:111], v[250:253], v[48:63]
	ds_read_b128 v[198:201], v32 offset:192
	ds_read_b128 v[202:205], v32 offset:208
	s_waitcnt lgkmcnt(4)
	v_cvt_pk_bf16_f32 v246, v206, v207
	v_cvt_pk_bf16_f32 v247, v208, v209
	v_cvt_pk_bf16_f32 v248, v234, v235
	v_cvt_pk_bf16_f32 v249, v236, v237
	s_nop 1
	v_mfma_f32_32x32x16_bf16 v[16:31], v[108:111], v[246:249], v[16:31]
	ds_read_b128 v[206:209], v32 offset:17088
	ds_read_b128 v[234:237], v32 offset:17104
	s_waitcnt lgkmcnt(4)
	v_cvt_pk_bf16_f32 v250, v238, v239
	v_cvt_pk_bf16_f32 v251, v240, v241
	v_cvt_pk_bf16_f32 v252, v242, v243
	v_cvt_pk_bf16_f32 v253, v244, v245
	s_nop 1
	v_mfma_f32_32x32x16_bf16 v[0:15], v[108:111], v[250:253], v[0:15]
	ds_read_b128 v[238:241], v32 offset:33984
	ds_read_b128 v[242:245], v32 offset:34000
	s_waitcnt vmcnt(4) lgkmcnt(4)
	v_cvt_pk_bf16_f32 v246, v198, v199
	v_cvt_pk_bf16_f32 v247, v200, v201
	v_cvt_pk_bf16_f32 v248, v202, v203
	v_cvt_pk_bf16_f32 v249, v204, v205
	s_nop 1
	v_mfma_f32_32x32x16_bf16 v[64:79], v[166:169], v[246:249], v[64:79]
	ds_read_b128 v[198:201], v32 offset:50880
	ds_read_b128 v[202:205], v32 offset:50896
	s_waitcnt lgkmcnt(4)
	v_cvt_pk_bf16_f32 v250, v206, v207
	v_cvt_pk_bf16_f32 v251, v208, v209
	v_cvt_pk_bf16_f32 v252, v234, v235
	v_cvt_pk_bf16_f32 v253, v236, v237
	s_nop 1
	v_mfma_f32_32x32x16_bf16 v[48:63], v[166:169], v[250:253], v[48:63]
	ds_read_b128 v[206:209], v32 offset:256
	ds_read_b128 v[234:237], v32 offset:272
	s_waitcnt lgkmcnt(4)
	v_cvt_pk_bf16_f32 v246, v238, v239
	v_cvt_pk_bf16_f32 v247, v240, v241
	v_cvt_pk_bf16_f32 v248, v242, v243
	v_cvt_pk_bf16_f32 v249, v244, v245
	s_nop 1
	v_mfma_f32_32x32x16_bf16 v[16:31], v[166:169], v[246:249], v[16:31]
	ds_read_b128 v[238:241], v32 offset:17152
	ds_read_b128 v[242:245], v32 offset:17168
	s_waitcnt lgkmcnt(4)
	v_cvt_pk_bf16_f32 v250, v198, v199
	v_cvt_pk_bf16_f32 v251, v200, v201
	v_cvt_pk_bf16_f32 v252, v202, v203
	v_cvt_pk_bf16_f32 v253, v204, v205
	s_nop 1
	v_mfma_f32_32x32x16_bf16 v[0:15], v[166:169], v[250:253], v[0:15]
	ds_read_b128 v[198:201], v32 offset:34048
	ds_read_b128 v[202:205], v32 offset:34064
	s_waitcnt vmcnt(3) lgkmcnt(4)
	v_cvt_pk_bf16_f32 v246, v206, v207
	v_cvt_pk_bf16_f32 v247, v208, v209
	v_cvt_pk_bf16_f32 v248, v234, v235
	v_cvt_pk_bf16_f32 v249, v236, v237
	s_nop 1
	v_mfma_f32_32x32x16_bf16 v[64:79], v[170:173], v[246:249], v[64:79]
	ds_read_b128 v[206:209], v32 offset:50944
	ds_read_b128 v[234:237], v32 offset:50960
	s_waitcnt lgkmcnt(4)
	v_cvt_pk_bf16_f32 v250, v238, v239
	v_cvt_pk_bf16_f32 v251, v240, v241
	v_cvt_pk_bf16_f32 v252, v242, v243
	v_cvt_pk_bf16_f32 v253, v244, v245
	s_nop 1
	v_mfma_f32_32x32x16_bf16 v[48:63], v[170:173], v[250:253], v[48:63]
	ds_read_b128 v[238:241], v32 offset:320
	ds_read_b128 v[242:245], v32 offset:336
	s_waitcnt lgkmcnt(4)
	v_cvt_pk_bf16_f32 v246, v198, v199
	v_cvt_pk_bf16_f32 v247, v200, v201
	v_cvt_pk_bf16_f32 v248, v202, v203
	v_cvt_pk_bf16_f32 v249, v204, v205
	s_nop 1
	v_mfma_f32_32x32x16_bf16 v[16:31], v[170:173], v[246:249], v[16:31]
	ds_read_b128 v[198:201], v32 offset:17216
	ds_read_b128 v[202:205], v32 offset:17232
	s_waitcnt lgkmcnt(4)
	v_cvt_pk_bf16_f32 v250, v206, v207
	v_cvt_pk_bf16_f32 v251, v208, v209
	v_cvt_pk_bf16_f32 v252, v234, v235
	v_cvt_pk_bf16_f32 v253, v236, v237
	s_nop 1
	v_mfma_f32_32x32x16_bf16 v[0:15], v[170:173], v[250:253], v[0:15]
	ds_read_b128 v[206:209], v32 offset:34112
	ds_read_b128 v[234:237], v32 offset:34128
	s_waitcnt vmcnt(2) lgkmcnt(4)
	v_cvt_pk_bf16_f32 v246, v238, v239
	v_cvt_pk_bf16_f32 v247, v240, v241
	v_cvt_pk_bf16_f32 v248, v242, v243
	v_cvt_pk_bf16_f32 v249, v244, v245
	s_nop 1
	v_mfma_f32_32x32x16_bf16 v[64:79], v[174:177], v[246:249], v[64:79]
	ds_read_b128 v[238:241], v32 offset:51008
	ds_read_b128 v[242:245], v32 offset:51024
	s_waitcnt lgkmcnt(4)
	v_cvt_pk_bf16_f32 v250, v198, v199
	v_cvt_pk_bf16_f32 v251, v200, v201
	v_cvt_pk_bf16_f32 v252, v202, v203
	v_cvt_pk_bf16_f32 v253, v204, v205
	s_nop 1
	v_mfma_f32_32x32x16_bf16 v[48:63], v[174:177], v[250:253], v[48:63]
	ds_read_b128 v[198:201], v32 offset:384
	ds_read_b128 v[202:205], v32 offset:400
	s_waitcnt lgkmcnt(4)
	v_cvt_pk_bf16_f32 v246, v206, v207
	v_cvt_pk_bf16_f32 v247, v208, v209
	v_cvt_pk_bf16_f32 v248, v234, v235
	v_cvt_pk_bf16_f32 v249, v236, v237
	s_nop 1
	v_mfma_f32_32x32x16_bf16 v[16:31], v[174:177], v[246:249], v[16:31]
	ds_read_b128 v[206:209], v32 offset:17280
	ds_read_b128 v[234:237], v32 offset:17296
	s_waitcnt lgkmcnt(4)
	v_cvt_pk_bf16_f32 v250, v238, v239
	v_cvt_pk_bf16_f32 v251, v240, v241
	v_cvt_pk_bf16_f32 v252, v242, v243
	v_cvt_pk_bf16_f32 v253, v244, v245
	s_nop 1
	v_mfma_f32_32x32x16_bf16 v[0:15], v[174:177], v[250:253], v[0:15]
	ds_read_b128 v[238:241], v32 offset:34176
	ds_read_b128 v[242:245], v32 offset:34192
	s_waitcnt vmcnt(1) lgkmcnt(4)
	v_cvt_pk_bf16_f32 v246, v198, v199
	v_cvt_pk_bf16_f32 v247, v200, v201
	v_cvt_pk_bf16_f32 v248, v202, v203
	v_cvt_pk_bf16_f32 v249, v204, v205
	s_nop 1
	v_mfma_f32_32x32x16_bf16 v[64:79], v[190:193], v[246:249], v[64:79]
	ds_read_b128 v[198:201], v32 offset:51072
	ds_read_b128 v[202:205], v32 offset:51088
	s_waitcnt lgkmcnt(4)
	v_cvt_pk_bf16_f32 v250, v206, v207
	v_cvt_pk_bf16_f32 v251, v208, v209
	v_cvt_pk_bf16_f32 v252, v234, v235
	v_cvt_pk_bf16_f32 v253, v236, v237
	s_nop 1
	v_mfma_f32_32x32x16_bf16 v[48:63], v[190:193], v[250:253], v[48:63]
	ds_read_b128 v[206:209], v32 offset:448
	ds_read_b128 v[234:237], v32 offset:464
	s_waitcnt lgkmcnt(4)
	v_cvt_pk_bf16_f32 v246, v238, v239
	v_cvt_pk_bf16_f32 v247, v240, v241
	v_cvt_pk_bf16_f32 v248, v242, v243
	v_cvt_pk_bf16_f32 v249, v244, v245
	s_nop 1
	v_mfma_f32_32x32x16_bf16 v[16:31], v[190:193], v[246:249], v[16:31]
	ds_read_b128 v[238:241], v32 offset:17344
	ds_read_b128 v[242:245], v32 offset:17360
	s_waitcnt lgkmcnt(4)
	v_cvt_pk_bf16_f32 v250, v198, v199
	v_cvt_pk_bf16_f32 v251, v200, v201
	v_cvt_pk_bf16_f32 v252, v202, v203
	v_cvt_pk_bf16_f32 v253, v204, v205
	s_nop 1
	v_mfma_f32_32x32x16_bf16 v[0:15], v[190:193], v[250:253], v[0:15]
	ds_read_b128 v[198:201], v32 offset:34240
	ds_read_b128 v[202:205], v32 offset:34256
	s_waitcnt vmcnt(0) lgkmcnt(4)
	v_cvt_pk_bf16_f32 v246, v206, v207
	v_cvt_pk_bf16_f32 v247, v208, v209
	v_cvt_pk_bf16_f32 v248, v234, v235
	v_cvt_pk_bf16_f32 v249, v236, v237
	s_nop 1
	v_mfma_f32_32x32x16_bf16 v[64:79], v[194:197], v[246:249], v[64:79]
	ds_read_b128 v[206:209], v32 offset:51136
	ds_read_b128 v[234:237], v32 offset:51152
	s_waitcnt lgkmcnt(4)
	v_cvt_pk_bf16_f32 v250, v238, v239
	v_cvt_pk_bf16_f32 v251, v240, v241
	v_cvt_pk_bf16_f32 v252, v242, v243
	v_cvt_pk_bf16_f32 v253, v244, v245
	s_nop 1
	v_mfma_f32_32x32x16_bf16 v[48:63], v[194:197], v[250:253], v[48:63]
	s_waitcnt lgkmcnt(2)
	v_cvt_pk_bf16_f32 v246, v198, v199
	v_cvt_pk_bf16_f32 v247, v200, v201
	v_cvt_pk_bf16_f32 v248, v202, v203
	v_cvt_pk_bf16_f32 v249, v204, v205
	s_nop 1
	v_mfma_f32_32x32x16_bf16 v[16:31], v[194:197], v[246:249], v[16:31]
	s_waitcnt lgkmcnt(0)
	v_cvt_pk_bf16_f32 v250, v206, v207
	v_cvt_pk_bf16_f32 v251, v208, v209
	v_cvt_pk_bf16_f32 v252, v234, v235
	v_cvt_pk_bf16_f32 v253, v236, v237
	s_nop 1
	v_mfma_f32_32x32x16_bf16 v[0:15], v[194:197], v[250:253], v[0:15]
	s_and_b64 s[30:31], s[10:11], exec
	s_cbranch_scc0 .Ls5_no_d1pf
	v_add_u32_e32 v34, 0x80, v119
	v_lshrrev_b32_e32 v35, 5, v34
	v_and_b32_e32 v34, 31, v34
	v_lshlrev_b32_e32 v34, 5, v34
	v_lshl_add_u32 v34, v35, 14, v34
	v_add_u32_e32 v34, 0x1000, v34
	v_mov_b32_e32 v35, v33
	v_lshl_add_u64 v[34:35], v[150:151], 0, v[34:35]
	global_load_dwordx4 v[166:169], v[34:35], off offset:-4096
	global_load_dwordx4 v[170:173], v[34:35], off offset:-3072
	global_load_dwordx4 v[174:177], v[34:35], off offset:-2048
	global_load_dwordx4 v[190:193], v[34:35], off offset:-1024
	global_load_dwordx4 v[194:197], v[34:35], off offset:0
	global_load_dwordx4 v[198:201], v[34:35], off offset:1024
	global_load_dwordx4 v[202:205], v[34:35], off offset:2048
	global_load_dwordx4 v[206:209], v[34:35], off offset:3072
.Ls5_no_d1pf:
	s_movk_i32 s88, 0x80
	s_mov_b64 s[10:11], 0
	s_and_b64 vcc, exec, s[8:9]
	s_barrier
	s_cbranch_vccz .LBB0_719
	s_ashr_i32 s8, s6, 5
	s_lshl_b32 s10, s8, 11
	s_lshl_b32 s7, s23, 5
	s_add_u32 s8, s14, s7
	s_addc_u32 s9, s15, 0
	v_or_b32_e32 v34, s10, v118
	v_add_u32_e32 v34, v34, v114
	v_lshlrev_b32_e32 v34, 10, v34
	v_bfe_u32 v35, v210, 5, 1
	v_lshl_add_u32 v34, v35, 4, v34
	v_mov_b32_e32 v35, 0
	v_lshl_add_u64 v[234:235], s[8:9], 0, v[34:35]
	v_mov_b32_e32 v34, 0x80000
	v_lshl_add_u64 v[236:237], v[234:235], 0, v[34:35]
	v_mov_b32_e32 v34, 0x100000
	v_lshl_add_u64 v[238:239], v[234:235], 0, v[34:35]
	v_mov_b32_e32 v34, 0x180000
	v_lshl_add_u64 v[240:241], v[234:235], 0, v[34:35]
	v_mov_b32_e32 v166, 0x3d372713
	v_mov_b32_e32 v167, 0x3d372713
	v_mov_b32_e32 v168, 0x3f4c422a
	v_mov_b32_e32 v169, 0x3f4c422a
	v_mov_b32_e32 v170, 0x3fb8aa3b
	v_mov_b32_e32 v171, 0x3fb8aa3b
	v_mov_b32_e32 v172, 0.5
	v_mov_b32_e32 v173, 0.5
	v_mov_b32_e32 v174, 1.0
	v_mov_b32_e32 v175, 1.0
	v_mov_b32_e32 v176, -2.0
	v_mov_b32_e32 v177, -2.0
	s_add_i32 s6, s6, s28
	s_add_i32 s17, s17, s28
	v_pk_mul_f32 v[190:191], v[166:167], v[64:65]
	v_pk_mul_f32 v[192:193], v[166:167], v[66:67]
	v_pk_mul_f32 v[194:195], v[166:167], v[68:69]
	v_pk_mul_f32 v[196:197], v[166:167], v[70:71]
	v_pk_mul_f32 v[190:191], v[64:65], v[190:191]
	v_pk_mul_f32 v[192:193], v[66:67], v[192:193]
	v_pk_mul_f32 v[194:195], v[68:69], v[194:195]
	v_pk_mul_f32 v[196:197], v[70:71], v[196:197]
	v_pk_fma_f32 v[190:191], v[64:65], v[190:191], v[64:65]
	v_pk_fma_f32 v[192:193], v[66:67], v[192:193], v[66:67]
	v_pk_fma_f32 v[194:195], v[68:69], v[194:195], v[68:69]
	v_pk_fma_f32 v[196:197], v[70:71], v[196:197], v[70:71]
	v_pk_mul_f32 v[190:191], v[168:169], v[190:191]
	v_pk_mul_f32 v[192:193], v[168:169], v[192:193]
	v_pk_mul_f32 v[194:195], v[168:169], v[194:195]
	v_pk_mul_f32 v[196:197], v[168:169], v[196:197]
	v_pk_add_f32 v[190:191], v[190:191], v[190:191]
	v_pk_add_f32 v[192:193], v[192:193], v[192:193]
	v_pk_add_f32 v[194:195], v[194:195], v[194:195]
	v_pk_add_f32 v[196:197], v[196:197], v[196:197]
	v_pk_mul_f32 v[190:191], v[170:171], v[190:191]
	v_pk_mul_f32 v[192:193], v[170:171], v[192:193]
	v_pk_mul_f32 v[194:195], v[170:171], v[194:195]
	v_pk_mul_f32 v[196:197], v[170:171], v[196:197]
	v_exp_f32_e32 v190, v190
	v_exp_f32_e32 v191, v191
	v_exp_f32_e32 v192, v192
	v_exp_f32_e32 v193, v193
	v_exp_f32_e32 v194, v194
	v_exp_f32_e32 v195, v195
	v_exp_f32_e32 v196, v196
	v_exp_f32_e32 v197, v197
	v_pk_mul_f32 v[64:65], v[172:173], v[64:65]
	v_pk_mul_f32 v[66:67], v[172:173], v[66:67]
	v_pk_mul_f32 v[68:69], v[172:173], v[68:69]
	v_pk_mul_f32 v[70:71], v[172:173], v[70:71]
	v_pk_add_f32 v[190:191], v[174:175], v[190:191]
	v_pk_add_f32 v[192:193], v[174:175], v[192:193]
	v_pk_add_f32 v[194:195], v[174:175], v[194:195]
	v_pk_add_f32 v[196:197], v[174:175], v[196:197]
	v_rcp_f32_e32 v190, v190
	v_rcp_f32_e32 v191, v191
	v_rcp_f32_e32 v192, v192
	v_rcp_f32_e32 v193, v193
	v_rcp_f32_e32 v194, v194
	v_rcp_f32_e32 v195, v195
	v_rcp_f32_e32 v196, v196
	v_rcp_f32_e32 v197, v197
	s_nop 0
	v_pk_fma_f32 v[190:191], v[190:191], v[176:177], v[174:175]
	v_pk_fma_f32 v[192:193], v[192:193], v[176:177], v[174:175]
	v_pk_fma_f32 v[194:195], v[194:195], v[176:177], v[174:175]
	v_pk_fma_f32 v[196:197], v[196:197], v[176:177], v[174:175]
	v_pk_add_f32 v[190:191], v[174:175], v[190:191]
	v_pk_add_f32 v[192:193], v[174:175], v[192:193]
	v_pk_add_f32 v[194:195], v[174:175], v[194:195]
	v_pk_add_f32 v[196:197], v[174:175], v[196:197]
	v_pk_mul_f32 v[64:65], v[64:65], v[190:191]
	v_pk_mul_f32 v[66:67], v[66:67], v[192:193]
	v_pk_mul_f32 v[68:69], v[68:69], v[194:195]
	v_pk_mul_f32 v[70:71], v[70:71], v[196:197]
	v_cvt_pk_bf16_f32 v198, v64, v65
	v_cvt_pk_bf16_f32 v199, v66, v67
	v_cvt_pk_bf16_f32 v200, v68, v69
	v_cvt_pk_bf16_f32 v201, v70, v71
	s_nop 1
	v_permlane32_swap_b32 v198, v200
	v_permlane32_swap_b32 v199, v201
	global_store_dwordx4 v[234:235], v[198:201], off
	v_pk_mul_f32 v[190:191], v[166:167], v[72:73]
	v_pk_mul_f32 v[192:193], v[166:167], v[74:75]
	v_pk_mul_f32 v[194:195], v[166:167], v[76:77]
	v_pk_mul_f32 v[196:197], v[166:167], v[78:79]
	v_pk_mul_f32 v[190:191], v[72:73], v[190:191]
	v_pk_mul_f32 v[192:193], v[74:75], v[192:193]
	v_pk_mul_f32 v[194:195], v[76:77], v[194:195]
	v_pk_mul_f32 v[196:197], v[78:79], v[196:197]
	v_pk_fma_f32 v[190:191], v[72:73], v[190:191], v[72:73]
	v_pk_fma_f32 v[192:193], v[74:75], v[192:193], v[74:75]
	v_pk_fma_f32 v[194:195], v[76:77], v[194:195], v[76:77]
	v_pk_fma_f32 v[196:197], v[78:79], v[196:197], v[78:79]
	v_pk_mul_f32 v[190:191], v[168:169], v[190:191]
	v_pk_mul_f32 v[192:193], v[168:169], v[192:193]
	v_pk_mul_f32 v[194:195], v[168:169], v[194:195]
	v_pk_mul_f32 v[196:197], v[168:169], v[196:197]
	v_pk_add_f32 v[190:191], v[190:191], v[190:191]
	v_pk_add_f32 v[192:193], v[192:193], v[192:193]
	v_pk_add_f32 v[194:195], v[194:195], v[194:195]
	v_pk_add_f32 v[196:197], v[196:197], v[196:197]
	v_pk_mul_f32 v[190:191], v[170:171], v[190:191]
	v_pk_mul_f32 v[192:193], v[170:171], v[192:193]
	v_pk_mul_f32 v[194:195], v[170:171], v[194:195]
	v_pk_mul_f32 v[196:197], v[170:171], v[196:197]
	v_exp_f32_e32 v190, v190
	v_exp_f32_e32 v191, v191
	v_exp_f32_e32 v192, v192
	v_exp_f32_e32 v193, v193
	v_exp_f32_e32 v194, v194
	v_exp_f32_e32 v195, v195
	v_exp_f32_e32 v196, v196
	v_exp_f32_e32 v197, v197
	v_pk_mul_f32 v[72:73], v[172:173], v[72:73]
	v_pk_mul_f32 v[74:75], v[172:173], v[74:75]
	v_pk_mul_f32 v[76:77], v[172:173], v[76:77]
	v_pk_mul_f32 v[78:79], v[172:173], v[78:79]
	v_pk_add_f32 v[190:191], v[174:175], v[190:191]
	v_pk_add_f32 v[192:193], v[174:175], v[192:193]
	v_pk_add_f32 v[194:195], v[174:175], v[194:195]
	v_pk_add_f32 v[196:197], v[174:175], v[196:197]
	v_rcp_f32_e32 v190, v190
	v_rcp_f32_e32 v191, v191
	v_rcp_f32_e32 v192, v192
	v_rcp_f32_e32 v193, v193
	v_rcp_f32_e32 v194, v194
	v_rcp_f32_e32 v195, v195
	v_rcp_f32_e32 v196, v196
	v_rcp_f32_e32 v197, v197
	s_nop 0
	v_pk_fma_f32 v[190:191], v[190:191], v[176:177], v[174:175]
	v_pk_fma_f32 v[192:193], v[192:193], v[176:177], v[174:175]
	v_pk_fma_f32 v[194:195], v[194:195], v[176:177], v[174:175]
	v_pk_fma_f32 v[196:197], v[196:197], v[176:177], v[174:175]
	v_pk_add_f32 v[190:191], v[174:175], v[190:191]
	v_pk_add_f32 v[192:193], v[174:175], v[192:193]
	v_pk_add_f32 v[194:195], v[174:175], v[194:195]
	v_pk_add_f32 v[196:197], v[174:175], v[196:197]
	v_pk_mul_f32 v[72:73], v[72:73], v[190:191]
	v_pk_mul_f32 v[74:75], v[74:75], v[192:193]
	v_pk_mul_f32 v[76:77], v[76:77], v[194:195]
	v_pk_mul_f32 v[78:79], v[78:79], v[196:197]
	v_cvt_pk_bf16_f32 v202, v72, v73
	v_cvt_pk_bf16_f32 v203, v74, v75
	v_cvt_pk_bf16_f32 v204, v76, v77
	v_cvt_pk_bf16_f32 v205, v78, v79
	s_nop 1
	v_permlane32_swap_b32 v202, v204
	v_permlane32_swap_b32 v203, v205
	global_store_dwordx4 v[234:235], v[202:205], off offset:1024
	v_pk_mul_f32 v[190:191], v[166:167], v[48:49]
	v_pk_mul_f32 v[192:193], v[166:167], v[50:51]
	v_pk_mul_f32 v[194:195], v[166:167], v[52:53]
	v_pk_mul_f32 v[196:197], v[166:167], v[54:55]
	v_pk_mul_f32 v[190:191], v[48:49], v[190:191]
	v_pk_mul_f32 v[192:193], v[50:51], v[192:193]
	v_pk_mul_f32 v[194:195], v[52:53], v[194:195]
	v_pk_mul_f32 v[196:197], v[54:55], v[196:197]
	v_pk_fma_f32 v[190:191], v[48:49], v[190:191], v[48:49]
	v_pk_fma_f32 v[192:193], v[50:51], v[192:193], v[50:51]
	v_pk_fma_f32 v[194:195], v[52:53], v[194:195], v[52:53]
	v_pk_fma_f32 v[196:197], v[54:55], v[196:197], v[54:55]
	v_pk_mul_f32 v[190:191], v[168:169], v[190:191]
	v_pk_mul_f32 v[192:193], v[168:169], v[192:193]
	v_pk_mul_f32 v[194:195], v[168:169], v[194:195]
	v_pk_mul_f32 v[196:197], v[168:169], v[196:197]
	v_pk_add_f32 v[190:191], v[190:191], v[190:191]
	v_pk_add_f32 v[192:193], v[192:193], v[192:193]
	v_pk_add_f32 v[194:195], v[194:195], v[194:195]
	v_pk_add_f32 v[196:197], v[196:197], v[196:197]
	v_pk_mul_f32 v[190:191], v[170:171], v[190:191]
	v_pk_mul_f32 v[192:193], v[170:171], v[192:193]
	v_pk_mul_f32 v[194:195], v[170:171], v[194:195]
	v_pk_mul_f32 v[196:197], v[170:171], v[196:197]
	v_exp_f32_e32 v190, v190
	v_exp_f32_e32 v191, v191
	v_exp_f32_e32 v192, v192
	v_exp_f32_e32 v193, v193
	v_exp_f32_e32 v194, v194
	v_exp_f32_e32 v195, v195
	v_exp_f32_e32 v196, v196
	v_exp_f32_e32 v197, v197
	v_pk_mul_f32 v[48:49], v[172:173], v[48:49]
	v_pk_mul_f32 v[50:51], v[172:173], v[50:51]
	v_pk_mul_f32 v[52:53], v[172:173], v[52:53]
	v_pk_mul_f32 v[54:55], v[172:173], v[54:55]
	v_pk_add_f32 v[190:191], v[174:175], v[190:191]
	v_pk_add_f32 v[192:193], v[174:175], v[192:193]
	v_pk_add_f32 v[194:195], v[174:175], v[194:195]
	v_pk_add_f32 v[196:197], v[174:175], v[196:197]
	v_rcp_f32_e32 v190, v190
	v_rcp_f32_e32 v191, v191
	v_rcp_f32_e32 v192, v192
	v_rcp_f32_e32 v193, v193
	v_rcp_f32_e32 v194, v194
	v_rcp_f32_e32 v195, v195
	v_rcp_f32_e32 v196, v196
	v_rcp_f32_e32 v197, v197
	s_nop 0
	v_pk_fma_f32 v[190:191], v[190:191], v[176:177], v[174:175]
	v_pk_fma_f32 v[192:193], v[192:193], v[176:177], v[174:175]
	v_pk_fma_f32 v[194:195], v[194:195], v[176:177], v[174:175]
	v_pk_fma_f32 v[196:197], v[196:197], v[176:177], v[174:175]
	v_pk_add_f32 v[190:191], v[174:175], v[190:191]
	v_pk_add_f32 v[192:193], v[174:175], v[192:193]
	v_pk_add_f32 v[194:195], v[174:175], v[194:195]
	v_pk_add_f32 v[196:197], v[174:175], v[196:197]
	v_pk_mul_f32 v[48:49], v[48:49], v[190:191]
	v_pk_mul_f32 v[50:51], v[50:51], v[192:193]
	v_pk_mul_f32 v[52:53], v[52:53], v[194:195]
	v_pk_mul_f32 v[54:55], v[54:55], v[196:197]
	v_cvt_pk_bf16_f32 v198, v48, v49
	v_cvt_pk_bf16_f32 v199, v50, v51
	v_cvt_pk_bf16_f32 v200, v52, v53
	v_cvt_pk_bf16_f32 v201, v54, v55
	s_nop 1
	v_permlane32_swap_b32 v198, v200
	v_permlane32_swap_b32 v199, v201
	global_store_dwordx4 v[236:237], v[198:201], off
	v_pk_mul_f32 v[190:191], v[166:167], v[56:57]
	v_pk_mul_f32 v[192:193], v[166:167], v[58:59]
	v_pk_mul_f32 v[194:195], v[166:167], v[60:61]
	v_pk_mul_f32 v[196:197], v[166:167], v[62:63]
	v_pk_mul_f32 v[190:191], v[56:57], v[190:191]
	v_pk_mul_f32 v[192:193], v[58:59], v[192:193]
	v_pk_mul_f32 v[194:195], v[60:61], v[194:195]
	v_pk_mul_f32 v[196:197], v[62:63], v[196:197]
	v_pk_fma_f32 v[190:191], v[56:57], v[190:191], v[56:57]
	v_pk_fma_f32 v[192:193], v[58:59], v[192:193], v[58:59]
	v_pk_fma_f32 v[194:195], v[60:61], v[194:195], v[60:61]
	v_pk_fma_f32 v[196:197], v[62:63], v[196:197], v[62:63]
	v_pk_mul_f32 v[190:191], v[168:169], v[190:191]
	v_pk_mul_f32 v[192:193], v[168:169], v[192:193]
	v_pk_mul_f32 v[194:195], v[168:169], v[194:195]
	v_pk_mul_f32 v[196:197], v[168:169], v[196:197]
	v_pk_add_f32 v[190:191], v[190:191], v[190:191]
	v_pk_add_f32 v[192:193], v[192:193], v[192:193]
	v_pk_add_f32 v[194:195], v[194:195], v[194:195]
	v_pk_add_f32 v[196:197], v[196:197], v[196:197]
	v_pk_mul_f32 v[190:191], v[170:171], v[190:191]
	v_pk_mul_f32 v[192:193], v[170:171], v[192:193]
	v_pk_mul_f32 v[194:195], v[170:171], v[194:195]
	v_pk_mul_f32 v[196:197], v[170:171], v[196:197]
	v_exp_f32_e32 v190, v190
	v_exp_f32_e32 v191, v191
	v_exp_f32_e32 v192, v192
	v_exp_f32_e32 v193, v193
	v_exp_f32_e32 v194, v194
	v_exp_f32_e32 v195, v195
	v_exp_f32_e32 v196, v196
	v_exp_f32_e32 v197, v197
	v_pk_mul_f32 v[56:57], v[172:173], v[56:57]
	v_pk_mul_f32 v[58:59], v[172:173], v[58:59]
	v_pk_mul_f32 v[60:61], v[172:173], v[60:61]
	v_pk_mul_f32 v[62:63], v[172:173], v[62:63]
	v_pk_add_f32 v[190:191], v[174:175], v[190:191]
	v_pk_add_f32 v[192:193], v[174:175], v[192:193]
	v_pk_add_f32 v[194:195], v[174:175], v[194:195]
	v_pk_add_f32 v[196:197], v[174:175], v[196:197]
	v_rcp_f32_e32 v190, v190
	v_rcp_f32_e32 v191, v191
	v_rcp_f32_e32 v192, v192
	v_rcp_f32_e32 v193, v193
	v_rcp_f32_e32 v194, v194
	v_rcp_f32_e32 v195, v195
	v_rcp_f32_e32 v196, v196
	v_rcp_f32_e32 v197, v197
	s_nop 0
	v_pk_fma_f32 v[190:191], v[190:191], v[176:177], v[174:175]
	v_pk_fma_f32 v[192:193], v[192:193], v[176:177], v[174:175]
	v_pk_fma_f32 v[194:195], v[194:195], v[176:177], v[174:175]
	v_pk_fma_f32 v[196:197], v[196:197], v[176:177], v[174:175]
	v_pk_add_f32 v[190:191], v[174:175], v[190:191]
	v_pk_add_f32 v[192:193], v[174:175], v[192:193]
	v_pk_add_f32 v[194:195], v[174:175], v[194:195]
	v_pk_add_f32 v[196:197], v[174:175], v[196:197]
	v_pk_mul_f32 v[56:57], v[56:57], v[190:191]
	v_pk_mul_f32 v[58:59], v[58:59], v[192:193]
	v_pk_mul_f32 v[60:61], v[60:61], v[194:195]
	v_pk_mul_f32 v[62:63], v[62:63], v[196:197]
	v_cvt_pk_bf16_f32 v202, v56, v57
	v_cvt_pk_bf16_f32 v203, v58, v59
	v_cvt_pk_bf16_f32 v204, v60, v61
	v_cvt_pk_bf16_f32 v205, v62, v63
	s_nop 1
	v_permlane32_swap_b32 v202, v204
	v_permlane32_swap_b32 v203, v205
	global_store_dwordx4 v[236:237], v[202:205], off offset:1024
	v_pk_mul_f32 v[190:191], v[166:167], v[16:17]
	v_pk_mul_f32 v[192:193], v[166:167], v[18:19]
	v_pk_mul_f32 v[194:195], v[166:167], v[20:21]
	v_pk_mul_f32 v[196:197], v[166:167], v[22:23]
	v_pk_mul_f32 v[190:191], v[16:17], v[190:191]
	v_pk_mul_f32 v[192:193], v[18:19], v[192:193]
	v_pk_mul_f32 v[194:195], v[20:21], v[194:195]
	v_pk_mul_f32 v[196:197], v[22:23], v[196:197]
	v_pk_fma_f32 v[190:191], v[16:17], v[190:191], v[16:17]
	v_pk_fma_f32 v[192:193], v[18:19], v[192:193], v[18:19]
	v_pk_fma_f32 v[194:195], v[20:21], v[194:195], v[20:21]
	v_pk_fma_f32 v[196:197], v[22:23], v[196:197], v[22:23]
	v_pk_mul_f32 v[190:191], v[168:169], v[190:191]
	v_pk_mul_f32 v[192:193], v[168:169], v[192:193]
	v_pk_mul_f32 v[194:195], v[168:169], v[194:195]
	v_pk_mul_f32 v[196:197], v[168:169], v[196:197]
	v_pk_add_f32 v[190:191], v[190:191], v[190:191]
	v_pk_add_f32 v[192:193], v[192:193], v[192:193]
	v_pk_add_f32 v[194:195], v[194:195], v[194:195]
	v_pk_add_f32 v[196:197], v[196:197], v[196:197]
	v_pk_mul_f32 v[190:191], v[170:171], v[190:191]
	v_pk_mul_f32 v[192:193], v[170:171], v[192:193]
	v_pk_mul_f32 v[194:195], v[170:171], v[194:195]
	v_pk_mul_f32 v[196:197], v[170:171], v[196:197]
	v_exp_f32_e32 v190, v190
	v_exp_f32_e32 v191, v191
	v_exp_f32_e32 v192, v192
	v_exp_f32_e32 v193, v193
	v_exp_f32_e32 v194, v194
	v_exp_f32_e32 v195, v195
	v_exp_f32_e32 v196, v196
	v_exp_f32_e32 v197, v197
	v_pk_mul_f32 v[16:17], v[172:173], v[16:17]
	v_pk_mul_f32 v[18:19], v[172:173], v[18:19]
	v_pk_mul_f32 v[20:21], v[172:173], v[20:21]
	v_pk_mul_f32 v[22:23], v[172:173], v[22:23]
	v_pk_add_f32 v[190:191], v[174:175], v[190:191]
	v_pk_add_f32 v[192:193], v[174:175], v[192:193]
	v_pk_add_f32 v[194:195], v[174:175], v[194:195]
	v_pk_add_f32 v[196:197], v[174:175], v[196:197]
	v_rcp_f32_e32 v190, v190
	v_rcp_f32_e32 v191, v191
	v_rcp_f32_e32 v192, v192
	v_rcp_f32_e32 v193, v193
	v_rcp_f32_e32 v194, v194
	v_rcp_f32_e32 v195, v195
	v_rcp_f32_e32 v196, v196
	v_rcp_f32_e32 v197, v197
	s_nop 0
	v_pk_fma_f32 v[190:191], v[190:191], v[176:177], v[174:175]
	v_pk_fma_f32 v[192:193], v[192:193], v[176:177], v[174:175]
	v_pk_fma_f32 v[194:195], v[194:195], v[176:177], v[174:175]
	v_pk_fma_f32 v[196:197], v[196:197], v[176:177], v[174:175]
	v_pk_add_f32 v[190:191], v[174:175], v[190:191]
	v_pk_add_f32 v[192:193], v[174:175], v[192:193]
	v_pk_add_f32 v[194:195], v[174:175], v[194:195]
	v_pk_add_f32 v[196:197], v[174:175], v[196:197]
	v_pk_mul_f32 v[16:17], v[16:17], v[190:191]
	v_pk_mul_f32 v[18:19], v[18:19], v[192:193]
	v_pk_mul_f32 v[20:21], v[20:21], v[194:195]
	v_pk_mul_f32 v[22:23], v[22:23], v[196:197]
	v_cvt_pk_bf16_f32 v198, v16, v17
	v_cvt_pk_bf16_f32 v199, v18, v19
	v_cvt_pk_bf16_f32 v200, v20, v21
	v_cvt_pk_bf16_f32 v201, v22, v23
	s_nop 1
	v_permlane32_swap_b32 v198, v200
	v_permlane32_swap_b32 v199, v201
	global_store_dwordx4 v[238:239], v[198:201], off
	v_pk_mul_f32 v[190:191], v[166:167], v[24:25]
	v_pk_mul_f32 v[192:193], v[166:167], v[26:27]
	v_pk_mul_f32 v[194:195], v[166:167], v[28:29]
	v_pk_mul_f32 v[196:197], v[166:167], v[30:31]
	v_pk_mul_f32 v[190:191], v[24:25], v[190:191]
	v_pk_mul_f32 v[192:193], v[26:27], v[192:193]
	v_pk_mul_f32 v[194:195], v[28:29], v[194:195]
	v_pk_mul_f32 v[196:197], v[30:31], v[196:197]
	v_pk_fma_f32 v[190:191], v[24:25], v[190:191], v[24:25]
	v_pk_fma_f32 v[192:193], v[26:27], v[192:193], v[26:27]
	v_pk_fma_f32 v[194:195], v[28:29], v[194:195], v[28:29]
	v_pk_fma_f32 v[196:197], v[30:31], v[196:197], v[30:31]
	v_pk_mul_f32 v[190:191], v[168:169], v[190:191]
	v_pk_mul_f32 v[192:193], v[168:169], v[192:193]
	v_pk_mul_f32 v[194:195], v[168:169], v[194:195]
	v_pk_mul_f32 v[196:197], v[168:169], v[196:197]
	v_pk_add_f32 v[190:191], v[190:191], v[190:191]
	v_pk_add_f32 v[192:193], v[192:193], v[192:193]
	v_pk_add_f32 v[194:195], v[194:195], v[194:195]
	v_pk_add_f32 v[196:197], v[196:197], v[196:197]
	v_pk_mul_f32 v[190:191], v[170:171], v[190:191]
	v_pk_mul_f32 v[192:193], v[170:171], v[192:193]
	v_pk_mul_f32 v[194:195], v[170:171], v[194:195]
	v_pk_mul_f32 v[196:197], v[170:171], v[196:197]
	v_exp_f32_e32 v190, v190
	v_exp_f32_e32 v191, v191
	v_exp_f32_e32 v192, v192
	v_exp_f32_e32 v193, v193
	v_exp_f32_e32 v194, v194
	v_exp_f32_e32 v195, v195
	v_exp_f32_e32 v196, v196
	v_exp_f32_e32 v197, v197
	v_pk_mul_f32 v[24:25], v[172:173], v[24:25]
	v_pk_mul_f32 v[26:27], v[172:173], v[26:27]
	v_pk_mul_f32 v[28:29], v[172:173], v[28:29]
	v_pk_mul_f32 v[30:31], v[172:173], v[30:31]
	v_pk_add_f32 v[190:191], v[174:175], v[190:191]
	v_pk_add_f32 v[192:193], v[174:175], v[192:193]
	v_pk_add_f32 v[194:195], v[174:175], v[194:195]
	v_pk_add_f32 v[196:197], v[174:175], v[196:197]
	v_rcp_f32_e32 v190, v190
	v_rcp_f32_e32 v191, v191
	v_rcp_f32_e32 v192, v192
	v_rcp_f32_e32 v193, v193
	v_rcp_f32_e32 v194, v194
	v_rcp_f32_e32 v195, v195
	v_rcp_f32_e32 v196, v196
	v_rcp_f32_e32 v197, v197
	s_nop 0
	v_pk_fma_f32 v[190:191], v[190:191], v[176:177], v[174:175]
	v_pk_fma_f32 v[192:193], v[192:193], v[176:177], v[174:175]
	v_pk_fma_f32 v[194:195], v[194:195], v[176:177], v[174:175]
	v_pk_fma_f32 v[196:197], v[196:197], v[176:177], v[174:175]
	v_pk_add_f32 v[190:191], v[174:175], v[190:191]
	v_pk_add_f32 v[192:193], v[174:175], v[192:193]
	v_pk_add_f32 v[194:195], v[174:175], v[194:195]
	v_pk_add_f32 v[196:197], v[174:175], v[196:197]
	v_pk_mul_f32 v[24:25], v[24:25], v[190:191]
	v_pk_mul_f32 v[26:27], v[26:27], v[192:193]
	v_pk_mul_f32 v[28:29], v[28:29], v[194:195]
	v_pk_mul_f32 v[30:31], v[30:31], v[196:197]
	v_cvt_pk_bf16_f32 v202, v24, v25
	v_cvt_pk_bf16_f32 v203, v26, v27
	v_cvt_pk_bf16_f32 v204, v28, v29
	v_cvt_pk_bf16_f32 v205, v30, v31
	s_nop 1
	v_permlane32_swap_b32 v202, v204
	v_permlane32_swap_b32 v203, v205
	global_store_dwordx4 v[238:239], v[202:205], off offset:1024
	v_pk_mul_f32 v[190:191], v[166:167], v[0:1]
	v_pk_mul_f32 v[192:193], v[166:167], v[2:3]
	v_pk_mul_f32 v[194:195], v[166:167], v[4:5]
	v_pk_mul_f32 v[196:197], v[166:167], v[6:7]
	v_pk_mul_f32 v[190:191], v[0:1], v[190:191]
	v_pk_mul_f32 v[192:193], v[2:3], v[192:193]
	v_pk_mul_f32 v[194:195], v[4:5], v[194:195]
	v_pk_mul_f32 v[196:197], v[6:7], v[196:197]
	v_pk_fma_f32 v[190:191], v[0:1], v[190:191], v[0:1]
	v_pk_fma_f32 v[192:193], v[2:3], v[192:193], v[2:3]
	v_pk_fma_f32 v[194:195], v[4:5], v[194:195], v[4:5]
	v_pk_fma_f32 v[196:197], v[6:7], v[196:197], v[6:7]
	v_pk_mul_f32 v[190:191], v[168:169], v[190:191]
	v_pk_mul_f32 v[192:193], v[168:169], v[192:193]
	v_pk_mul_f32 v[194:195], v[168:169], v[194:195]
	v_pk_mul_f32 v[196:197], v[168:169], v[196:197]
	v_pk_add_f32 v[190:191], v[190:191], v[190:191]
	v_pk_add_f32 v[192:193], v[192:193], v[192:193]
	v_pk_add_f32 v[194:195], v[194:195], v[194:195]
	v_pk_add_f32 v[196:197], v[196:197], v[196:197]
	v_pk_mul_f32 v[190:191], v[170:171], v[190:191]
	v_pk_mul_f32 v[192:193], v[170:171], v[192:193]
	v_pk_mul_f32 v[194:195], v[170:171], v[194:195]
	v_pk_mul_f32 v[196:197], v[170:171], v[196:197]
	v_exp_f32_e32 v190, v190
	v_exp_f32_e32 v191, v191
	v_exp_f32_e32 v192, v192
	v_exp_f32_e32 v193, v193
	v_exp_f32_e32 v194, v194
	v_exp_f32_e32 v195, v195
	v_exp_f32_e32 v196, v196
	v_exp_f32_e32 v197, v197
	v_pk_mul_f32 v[0:1], v[172:173], v[0:1]
	v_pk_mul_f32 v[2:3], v[172:173], v[2:3]
	v_pk_mul_f32 v[4:5], v[172:173], v[4:5]
	v_pk_mul_f32 v[6:7], v[172:173], v[6:7]
	v_pk_add_f32 v[190:191], v[174:175], v[190:191]
	v_pk_add_f32 v[192:193], v[174:175], v[192:193]
	v_pk_add_f32 v[194:195], v[174:175], v[194:195]
	v_pk_add_f32 v[196:197], v[174:175], v[196:197]
	v_rcp_f32_e32 v190, v190
	v_rcp_f32_e32 v191, v191
	v_rcp_f32_e32 v192, v192
	v_rcp_f32_e32 v193, v193
	v_rcp_f32_e32 v194, v194
	v_rcp_f32_e32 v195, v195
	v_rcp_f32_e32 v196, v196
	v_rcp_f32_e32 v197, v197
	s_nop 0
	v_pk_fma_f32 v[190:191], v[190:191], v[176:177], v[174:175]
	v_pk_fma_f32 v[192:193], v[192:193], v[176:177], v[174:175]
	v_pk_fma_f32 v[194:195], v[194:195], v[176:177], v[174:175]
	v_pk_fma_f32 v[196:197], v[196:197], v[176:177], v[174:175]
	v_pk_add_f32 v[190:191], v[174:175], v[190:191]
	v_pk_add_f32 v[192:193], v[174:175], v[192:193]
	v_pk_add_f32 v[194:195], v[174:175], v[194:195]
	v_pk_add_f32 v[196:197], v[174:175], v[196:197]
	v_pk_mul_f32 v[0:1], v[0:1], v[190:191]
	v_pk_mul_f32 v[2:3], v[2:3], v[192:193]
	v_pk_mul_f32 v[4:5], v[4:5], v[194:195]
	v_pk_mul_f32 v[6:7], v[6:7], v[196:197]
	v_cvt_pk_bf16_f32 v198, v0, v1
	v_cvt_pk_bf16_f32 v199, v2, v3
	v_cvt_pk_bf16_f32 v200, v4, v5
	v_cvt_pk_bf16_f32 v201, v6, v7
	s_nop 1
	v_permlane32_swap_b32 v198, v200
	v_permlane32_swap_b32 v199, v201
	global_store_dwordx4 v[240:241], v[198:201], off
	v_pk_mul_f32 v[190:191], v[166:167], v[8:9]
	v_pk_mul_f32 v[192:193], v[166:167], v[10:11]
	v_pk_mul_f32 v[194:195], v[166:167], v[12:13]
	v_pk_mul_f32 v[196:197], v[166:167], v[14:15]
	v_pk_mul_f32 v[190:191], v[8:9], v[190:191]
	v_pk_mul_f32 v[192:193], v[10:11], v[192:193]
	v_pk_mul_f32 v[194:195], v[12:13], v[194:195]
	v_pk_mul_f32 v[196:197], v[14:15], v[196:197]
	v_pk_fma_f32 v[190:191], v[8:9], v[190:191], v[8:9]
	v_pk_fma_f32 v[192:193], v[10:11], v[192:193], v[10:11]
	v_pk_fma_f32 v[194:195], v[12:13], v[194:195], v[12:13]
	v_pk_fma_f32 v[196:197], v[14:15], v[196:197], v[14:15]
	v_pk_mul_f32 v[190:191], v[168:169], v[190:191]
	v_pk_mul_f32 v[192:193], v[168:169], v[192:193]
	v_pk_mul_f32 v[194:195], v[168:169], v[194:195]
	v_pk_mul_f32 v[196:197], v[168:169], v[196:197]
	v_pk_add_f32 v[190:191], v[190:191], v[190:191]
	v_pk_add_f32 v[192:193], v[192:193], v[192:193]
	v_pk_add_f32 v[194:195], v[194:195], v[194:195]
	v_pk_add_f32 v[196:197], v[196:197], v[196:197]
	v_pk_mul_f32 v[190:191], v[170:171], v[190:191]
	v_pk_mul_f32 v[192:193], v[170:171], v[192:193]
	v_pk_mul_f32 v[194:195], v[170:171], v[194:195]
	v_pk_mul_f32 v[196:197], v[170:171], v[196:197]
	v_exp_f32_e32 v190, v190
	v_exp_f32_e32 v191, v191
	v_exp_f32_e32 v192, v192
	v_exp_f32_e32 v193, v193
	v_exp_f32_e32 v194, v194
	v_exp_f32_e32 v195, v195
	v_exp_f32_e32 v196, v196
	v_exp_f32_e32 v197, v197
	v_pk_mul_f32 v[8:9], v[172:173], v[8:9]
	v_pk_mul_f32 v[10:11], v[172:173], v[10:11]
	v_pk_mul_f32 v[12:13], v[172:173], v[12:13]
	v_pk_mul_f32 v[14:15], v[172:173], v[14:15]
	v_pk_add_f32 v[190:191], v[174:175], v[190:191]
	v_pk_add_f32 v[192:193], v[174:175], v[192:193]
	v_pk_add_f32 v[194:195], v[174:175], v[194:195]
	v_pk_add_f32 v[196:197], v[174:175], v[196:197]
	v_rcp_f32_e32 v190, v190
	v_rcp_f32_e32 v191, v191
	v_rcp_f32_e32 v192, v192
	v_rcp_f32_e32 v193, v193
	v_rcp_f32_e32 v194, v194
	v_rcp_f32_e32 v195, v195
	v_rcp_f32_e32 v196, v196
	v_rcp_f32_e32 v197, v197
	s_nop 0
	v_pk_fma_f32 v[190:191], v[190:191], v[176:177], v[174:175]
	v_pk_fma_f32 v[192:193], v[192:193], v[176:177], v[174:175]
	v_pk_fma_f32 v[194:195], v[194:195], v[176:177], v[174:175]
	v_pk_fma_f32 v[196:197], v[196:197], v[176:177], v[174:175]
	v_pk_add_f32 v[190:191], v[174:175], v[190:191]
	v_pk_add_f32 v[192:193], v[174:175], v[192:193]
	v_pk_add_f32 v[194:195], v[174:175], v[194:195]
	v_pk_add_f32 v[196:197], v[174:175], v[196:197]
	v_pk_mul_f32 v[8:9], v[8:9], v[190:191]
	v_pk_mul_f32 v[10:11], v[10:11], v[192:193]
	v_pk_mul_f32 v[12:13], v[12:13], v[194:195]
	v_pk_mul_f32 v[14:15], v[14:15], v[196:197]
	v_cvt_pk_bf16_f32 v202, v8, v9
	v_cvt_pk_bf16_f32 v203, v10, v11
	v_cvt_pk_bf16_f32 v204, v12, v13
	v_cvt_pk_bf16_f32 v205, v14, v15
	s_nop 1
	v_permlane32_swap_b32 v202, v204
	v_permlane32_swap_b32 v203, v205
	global_store_dwordx4 v[240:241], v[202:205], off offset:1024
	s_cmpk_gt_i32 s6, 0x1ff
	s_cbranch_scc0 .LBB0_718
